# shared barrier routine: the L1 invalidate is issued while the workgroup waits for the release instead of after it
# speedup vs baseline: 1.0340x; 1.0333x over previous
.Lmybar:
	v_readlane_b32 s100, v240, 35
	v_readlane_b32 s101, v240, 36
	v_mov_b32_e32 v247, 0x23fc0
	ds_read2_b32 v[248:249], v247 offset1:1
	v_mov_b32_e32 v250, s56
	v_lshlrev_b32_e32 v250, 8, v250
	v_add_u32_e32 v250, 0x1400, v250
	v_mov_b32_e32 v251, 1
	s_add_u32 s98, s98, 1
	s_waitcnt vmcnt(0)
	s_nop 1
	global_atomic_add v252, v250, v251, s[100:101] sc0
	s_waitcnt vmcnt(0) lgkmcnt(0)
	v_mul_lo_u32 v253, v248, s98
	v_add_u32_e32 v252, 1, v252
	v_add_u32_e32 v254, 0x1000, v250
	v_cmp_eq_u32_e32 vcc, v252, v253
	s_cbranch_vccz .Lmb_local
	buffer_wbl2 sc1
	s_waitcnt vmcnt(0)
	v_mov_b32_e32 v250, 0x3400
	global_atomic_add v250, v251, s[100:101]
	buffer_inv sc1
	v_mul_lo_u32 v253, v249, s98
	v_mov_b32_e32 v255, 0

.Lmb_top_ok:
	global_atomic_add v254, v251, s[100:101]
	s_waitcnt vmcnt(0)
	s_branch .Lmb_done
.Lmb_local:
	buffer_inv sc1
	v_mov_b32_e32 v255, 0
	v_mov_b32_e32 v253, s98
.Lmb_spin_loc:
	global_load_dword v252, v254, s[100:101] sc1
	s_waitcnt vmcnt(0)
	v_cmp_lt_u32_e32 vcc, v252, v253
	s_cbranch_vccz .Lmb_loc_ok
	s_sleep 1
	v_add_u32_e32 v255, 1, v255
	v_cmp_gt_u32_e32 vcc, 0x40000, v255
	s_cbranch_vccnz .Lmb_spin_loc
.Lmb_loc_ok:
	s_waitcnt vmcnt(0)
.Lmb_done:
	s_cmp_eq_u32 s99, 2
	s_cbranch_scc1 .Lmybar_ret2
	s_cmp_eq_u32 s99, 3
	s_cbranch_scc1 .Lmybar_ret3
	s_cmp_eq_u32 s99, 4
	s_cbranch_scc1 .Lmybar_ret4
	s_cmp_eq_u32 s99, 5
	s_cbranch_scc1 .Lmybar_ret5
	s_cmp_eq_u32 s99, 6
	s_cbranch_scc1 .Lmybar_ret6
	s_cmp_eq_u32 s99, 7
	s_cbranch_scc1 .Lmybar_ret7
	s_cmp_eq_u32 s99, 8
	s_cbranch_scc1 .Lmybar_ret8
	s_cmp_eq_u32 s99, 9
	s_cbranch_scc1 .Lmybar_ret9
	s_cmp_eq_u32 s99, 10
	s_cbranch_scc1 .Lmybar_ret10
	s_cmp_eq_u32 s99, 11
	s_cbranch_scc1 .Lmybar_ret11
	s_branch .Lmybar_ret12
